# MLA phase: static priority raise for waves 0-3 (the other half; waves 4-7 was null)
# speedup vs baseline: 1.0113x; 1.0113x over previous
; #define LAS __attribute__((address_space(3)))
; #define PHASE() size_t z_ = 0; asm volatile("" : "+s"(z_)); unsigned char* ws = args.ws + z_; float* H = args.out + z_; (void)H; (void)ws;
; #define RELANE() int tid = threadIdx.x; asm volatile("" : "+v"(tid)); const int lane = tid & 63; (void)lane;
; __device__ __forceinline__ void mla_unit(LAS unsigned char* lds, int bh, int x, const bf16* QM, const bf16* KM, const bf16* VMT, bf16* OUT, ssq_t* SSo, int tid, int lane, int wave) {
;     const int r32 = lane & 31, hi = lane >> 5, g = wave >> 2, wq = wave & 3;
;     const int q0 = 128 * x, qg = q0 + 32 * wq + r32, T = 2 * (x + 1);
;     LAS bf16* L = (LAS bf16*)lds;
;     LAS bf16* Qs = L + MLA_QOFF;
;     const LAS bf16* Qw = Qs + (32 * wq + r32) * 200 + 8 * hi;
;     const LAS bf16* Kw = L + MLA_KOFF + g * MLA_KS + r32 * 200 + 8 * hi;
;     const LAS bf16* Vw = L + MLA_VOFF + g * MLA_VS + r32 * 36 + 4 * hi;
;     f32x16 o[4];
; #pragma unroll
;     for (int k = 0; k < 4; ++k)
; #pragma unroll
;         for (int r = 0; r < 16; ++r) o[k][r] = 0.f;
;     float mref = 0.f, lrun = 0.f;
;     const bf16* Kb = KM + (size_t)bh * S * 192;
;     const bf16* Vb = VMT + (size_t)bh * 128 * S;
;     u32x4 rk0[3], rv0[2], rk1[3], rv1[2];
;     const unsigned kgo = (unsigned)tid * 16u;
;     const unsigned vgo = (unsigned)((tid >> 3) * S + (tid & 7) * 8) * 2u;
;     unsigned kds[3];
; #pragma unroll
;     for (int i = 0; i < 3; ++i) { const int c = tid + 512 * i, row = c / 24, ch = c - 24 * row; kds[i] = (unsigned)(MLA_KOFF + (row >> 5) * MLA_KS + (row & 31) * 200 + ch * 8); }
;     const unsigned vds = (unsigned)(MLA_VOFF + ((tid & 7) >> 2) * MLA_VS + (tid >> 3) * 36 + (tid & 3) * 8);
; __global__ void __launch_bounds__(512, 2) hybrid_fwd(Args args) {
;     ...
;         { RELANE(); PHASE();
;         for (int i = vcu2; i < 512; i += G) { const int round = i >> 8, v = i & 255, bh = v >> 5, s = v & 31, x = round == 0 ? 63 - s : s; mla_unit(lds, bh, x, QM, KM, VMT, MIXRAW, SSP(layer * 8 + 7), tid, lane, wave); } }
.LBB0_1281:
	v_readlane_b32 s6, v255, 52
	v_readlane_b32 s7, v255, 53
	v_mov_b32_e32 v2, v194
	s_mov_b64 s[2:3], 0
	s_andn2_b64 vcc, exec, s[6:7]
	s_cbranch_vccnz .LBB0_1320
	v_readlane_b32 s10, v252, 7
	v_readlane_b32 s11, v252, 8
	s_add_u32 s6, s10, s2
	s_addc_u32 s7, s11, s3
	s_add_u32 s13, s6, 0x8500000
	s_addc_u32 s34, s7, 0
	v_readlane_b32 s8, v255, 46
	s_add_u32 s35, s6, 0x9d00000
	v_readlane_b32 s9, v255, 47
	s_addc_u32 s36, s7, 0
	s_lshl_b64 s[8:9], s[8:9], 3
	s_add_u32 s4, s6, s8
	s_addc_u32 s8, s7, s9
	v_and_b32_e32 v3, 31, v2
	v_bfe_u32 v4, v2, 5, 1
	v_readlane_b32 s1, v253, 48
	s_add_u32 s37, s4, 0x105f0000
	v_lshlrev_b32_e32 v15, 3, v4
	v_or_b32_e32 v165, s1, v3
	v_mul_u32_u24_e32 v7, 0x190, v3
	v_mul_u32_u24_e32 v16, 0x48, v3
	v_lshlrev_b32_e32 v164, 2, v4
	v_lshlrev_b32_e32 v3, 4, v4
	v_and_b32_e32 v4, 7, v2
	s_mov_b32 s14, 0x2aaaaaab
	s_addc_u32 s40, s8, 0
	v_mul_u32_u24_e32 v5, 0x190, v165
	s_add_i32 s4, 0, 0x1a000
	v_lshlrev_b32_e32 v18, 4, v4
	v_mul_hi_i32 v4, v2, s14
	v_add3_u32 v208, s4, v5, v3
	v_lshrrev_b32_e32 v5, 31, v4
	v_ashrrev_i32_e32 v4, 2, v4
	v_add_u32_e32 v11, v4, v5
	s_movk_i32 s15, 0xffe8
	v_mad_u64_u32 v[4:5], s[8:9], v11, s15, v[2:3]
	v_lshrrev_b32_e32 v5, 5, v11
	v_and_b32_e32 v6, 31, v11
	v_mul_i32_i24_e32 v5, 0x1900, v5
	v_mul_u32_u24_e32 v6, 0xc8, v6
	v_lshlrev_b32_e32 v8, 3, v4
	v_add3_u32 v19, v5, v6, v8
	v_add_u32_e32 v6, 0x200, v2
	v_mul_hi_i32 v5, v6, s14
	v_lshrrev_b32_e32 v8, 31, v5
	v_ashrrev_i32_e32 v5, 2, v5
	v_add_u32_e32 v5, v5, v8
	v_mad_u64_u32 v[8:9], s[8:9], v5, s15, v[6:7]
	v_lshrrev_b32_e32 v9, 5, v5
	v_and_b32_e32 v10, 31, v5
	v_mul_i32_i24_e32 v9, 0x1900, v9
	v_mul_u32_u24_e32 v10, 0xc8, v10
	v_lshlrev_b32_e32 v12, 3, v8
	v_add3_u32 v9, v9, v10, v12
	v_add_u32_e32 v10, 0x400, v2
	v_mul_hi_i32 v12, v10, s14
	v_lshrrev_b32_e32 v13, 31, v12
	v_ashrrev_i32_e32 v12, 2, v12
	v_add_u32_e32 v20, v12, v13
	v_mad_u64_u32 v[12:13], s[8:9], v20, s15, v[10:11]
	v_lshrrev_b32_e32 v13, 5, v20
	v_and_b32_e32 v14, 31, v20
	v_readlane_b32 s1, v253, 46
	v_mul_i32_i24_e32 v13, 0x1900, v13
	v_mul_u32_u24_e32 v14, 0xc8, v14
	v_lshlrev_b32_e32 v21, 3, v12
	v_add3_u32 v209, s1, v7, v3
	v_lshlrev_b32_e32 v3, 3, v2
	v_add3_u32 v13, v13, v14, v21
	v_and_b32_e32 v14, 24, v3
	v_ashrrev_i32_e32 v3, 31, v2
	s_movk_i32 s1, 0x190
	v_lshlrev_b64 v[166:167], 4, v[2:3]
	v_mul_lo_u32 v3, v11, s1
	v_add_u32_e32 v22, s4, v3
	v_ashrrev_i32_e32 v7, 31, v6
	v_mul_lo_u32 v3, v5, s1
	v_lshlrev_b32_e32 v23, 4, v4
	v_lshlrev_b64 v[168:169], 4, v[6:7]
	v_add_u32_e32 v6, s4, v3
	v_mul_lo_u32 v3, v20, s1
	v_add_u32_e32 v4, 0x600, v2
	v_lshlrev_b32_e32 v7, 4, v8
	v_add_u32_e32 v8, s4, v3
	v_mul_hi_i32 v3, v4, s14
	v_lshrrev_b32_e32 v5, 31, v3
	v_ashrrev_i32_e32 v3, 2, v3
	v_ashrrev_i32_e32 v11, 31, v10
	v_add_u32_e32 v3, v3, v5
	v_lshlrev_b64 v[170:171], 4, v[10:11]
	v_mul_lo_u32 v11, v3, s15
	v_ashrrev_i32_e32 v5, 31, v4
	v_lshlrev_b64 v[172:173], 4, v[4:5]
	v_mul_lo_u32 v3, v3, s1
	v_add_lshl_u32 v11, v11, v4, 4
	v_add_u32_e32 v4, 0x800, v2
	v_lshlrev_b32_e32 v10, 4, v12
	v_add_u32_e32 v12, s4, v3
	v_mul_hi_i32 v3, v4, s14
	v_lshrrev_b32_e32 v5, 31, v3
	v_ashrrev_i32_e32 v3, 2, v3
	v_add_u32_e32 v3, v3, v5
	v_mul_lo_u32 v20, v3, s15
	v_ashrrev_i32_e32 v5, 31, v4
	v_lshlrev_b64 v[174:175], 4, v[4:5]
	v_mul_lo_u32 v3, v3, s1
	v_add_lshl_u32 v20, v20, v4, 4
	v_add_u32_e32 v4, 0xa00, v2
	v_add_u32_e32 v24, s4, v3
	v_mul_hi_i32 v3, v4, s14
	v_lshrrev_b32_e32 v5, 31, v3
	v_ashrrev_i32_e32 v3, 2, v3
	v_add_u32_e32 v3, v3, v5
	v_ashrrev_i32_e32 v17, 3, v2
	v_bfe_u32 v21, v2, 2, 1
	v_mul_lo_u32 v25, v3, s15
	v_ashrrev_i32_e32 v5, 31, v4
	v_mul_lo_u32 v3, v3, s1
	v_and_b32_e32 v1, 63, v2
	v_lshlrev_b64 v[176:177], 4, v[4:5]
	v_add_u32_e32 v5, s4, v3
	v_lshlrev_b32_e32 v178, 4, v2
	v_mul_u32_u24_e32 v21, 0x1200, v21
	v_readlane_b32 s1, v253, 47
	v_mad_u64_u32 v[2:3], s[8:9], v17, 36, v[14:15]
	s_nop 0
	v_add3_u32 v210, s1, v16, v15
	v_add_lshl_u32 v2, v2, v21, 1
	v_readlane_b32 s1, v255, 26
	v_lshl_or_b32 v98, v17, 14, v18
	v_add_u32_e32 v214, 0, v2
	v_add_u32_e32 v2, s1, v2
	v_add_lshl_u32 v4, v25, v4, 4
	v_mov_b32_e32 v179, v99
	v_add_u32_e32 v215, 0xc800, v2
	v_readlane_b32 s1, v253, 49
	v_lshl_add_u64 v[2:3], s[6:7], 0, v[98:99]
	s_mov_b64 s[8:9], 0xb500000
	v_lshl_add_u32 v211, v19, 1, 0
	v_lshl_add_u32 v212, v9, 1, 0
	v_lshl_add_u32 v213, v13, 1, 0
	v_lshl_add_u32 v216, v1, 2, s1
	v_cmp_gt_u32_e64 s[42:43], 32, v1
	v_lshl_add_u64 v[180:181], v[2:3], 0, s[8:9]
	v_lshl_add_u64 v[182:183], s[10:11], 0, v[98:99]
	v_lshl_add_u64 v[184:185], s[10:11], 0, v[178:179]
	v_add_u32_e32 v217, v22, v23
	v_add_u32_e32 v218, v6, v7
	v_add_u32_e32 v219, v8, v10
	v_add_u32_e32 v220, v12, v11
	v_add_u32_e32 v221, v24, v20
	v_add_u32_e32 v222, v5, v4
	v_readfirstlane_b32 s1, v194
	s_cmpk_ge_u32 s1, 0x100
	s_cbranch_scc1 .Lmla_prio_skip
	s_setprio 1
